# static s_setprio 1 for waves 0-3 (instead of 4-7) during mLSTM and attention phases
# baseline (speedup 1.0000x reference)
; #define LAS __attribute__((address_space(3)))
; __device__ __forceinline__ void p2_mlstm(const Params& p, LAS unsigned char* lds) {
;     const int tid = threadIdx.x, wid = __builtin_amdgcn_readfirstlane(tid >> 6), lane = tid & 63, r = lane & 15, q = lane >> 4;
;     unsigned char* ws = p.ws;
;     const bf16_t* R1 = (const bf16_t*)(ws + WS_R1); const bf16_t* QK = (const bf16_t*)(ws + WS_R2);
;     const float* GATES = (const float*)(ws + WS_GATES);
;     float* SSQ = (float*)(ws + WS_SSQ);
;     bf16_t* HM = (bf16_t*)((unsigned char*)p.out + OUT_HM);
;     LAS unsigned char* KB = lds + ML_KB; LAS unsigned char* VT = lds + ML_VT; LAS unsigned char* CT = lds + ML_CT; LAS unsigned char* WVT = lds + ML_WVT;
;     LAS unsigned char* NV = lds + 149760;
;     LAS unsigned char* WV = lds + 150272;
;     LAS float* PU = (LAS float*)(lds + ML_G); LAS float* PCM = PU + 2048; LAS float* PB = PU + 4096; LAS float* PBT = PU + 6144; LAS float* PCT = PBT + 16; LAS float* MPREV = PBT + 32; LAS float* MM127 = PBT + 48;
;     for (int it = blockIdx.x; it < 256; it += gridDim.x) {
.LBB0_233:
	s_cmp_lt_i32 s90, 4
	s_cselect_b64 s[0:1], -1, 0
	s_add_u32 s4, s74, 0x2000000
	s_addc_u32 s5, s75, 0
	v_writelane_b32 v254, s4, 23
	s_and_b64 s[0:1], s[0:1], s[2:3]
	s_nop 0
	v_writelane_b32 v254, s5, 24
	v_writelane_b32 v254, s0, 25
	s_andn2_b64 vcc, exec, s[0:1]
	s_nop 0
	v_writelane_b32 v254, s1, 26
	s_cbranch_vccnz .LBB0_359
	s_cmpk_gt_i32 s84, 0xff
	v_readfirstlane_b32 s0, v212
	s_cbranch_scc1 .LBB0_359
	s_cmp_ge_u32 s0, 0x100
	s_cbranch_scc1 .Lprio3_done
	s_setprio 1

; #define LAS __attribute__((address_space(3)))
; __device__ __forceinline__ void p4_attn(const Params& p, LAS unsigned char* lds, const int dummy) {
;     const int tid = threadIdx.x, wid = __builtin_amdgcn_readfirstlane(tid >> 6), lane = tid & 63, r = lane & 15, q = lane >> 4;
;     unsigned char* ws = p.ws;
;     bf16_t* R1 = (bf16_t*)(ws + WS_R1);
;     const float* RC = (const float*)(ws + WS_ROPE); const float* RS = RC + 2048 * 16;
;     float* ML = (float*)((unsigned char*)p.out + OUT_ML);
;     LAS unsigned char* KA = lds + AT_KA; LAS unsigned char* VB = lds + AT_VB;
;     const float QSCALE = 0.08838834764831845f * 1.4426950408889634f;
;     u32x4 kr[8], vr[8];
;     int it = blockIdx.x;
;     if (it < 1536) { const AttnItem a0 = attn_item(it); attn_load(R1, a0, tid, kr, vr); }
.LBB0_570:
	s_mov_b32 s99, 0
	s_cmp_lt_i32 s90, 6
	s_cselect_b64 s[0:1], -1, 0
	s_and_b64 s[96:97], s[0:1], s[2:3]
	s_andn2_b64 vcc, exec, s[96:97]
	s_cbranch_vccnz .LBB0_629
	v_readfirstlane_b32 s100, v212
	s_nop 3
	s_cmp_ge_u32 s100, 0x100
	s_cbranch_scc1 .Lprio5_done
	s_setprio 1
